# speedup vs baseline: 1.0026x; 1.0026x over previous
; #define MFMA32(a, b, c) __builtin_amdgcn_mfma_f32_32x32x16_bf16((a), (b), (c), 0, 0, 0)
; DI void finishSM(f32x16& p0, f32x16& p1, float alpha, float& l_reg, bf16x8& pa0, bf16x8& pa1, bf16x8& pa2, bf16x8& pa3) {
; #pragma unroll
;     for (int r = 0; r < 16; ++r) p1[r] = __builtin_amdgcn_exp2f(p1[r]);
;     float ps = 0;
; #pragma unroll
;     for (int r = 0; r < 16; ++r) ps += p0[r];
; #pragma unroll
;     for (int r = 0; r < 16; ++r) ps += p1[r];
;     { auto rr = __builtin_amdgcn_permlane32_swap(__float_as_uint(ps), __float_as_uint(ps), false, false);
;       ps = __uint_as_float(rr[0]) + __uint_as_float(rr[1]); }
;     l_reg = l_reg * alpha + ps;
;     ...
;     PK4(p0, 0, pa0); PK4(p0, 8, pa1); PK4(p1, 0, pa2); PK4(p1, 8, pa3);
;     ...
; }
; template <int KB>
; DI void qkt(f32x16& p0, f32x16& p1, const char* K_lds, int r32, int hi, const bf16x8* qr, const float* bb) {
; #pragma unroll
;     for (int g = 0; g < 4; ++g) {
;         const f32x4 b0 = *(const f32x4*)(bb + KB * 64 + 8 * g), b1 = *(const f32x4*)(bb + KB * 64 + 32 + 8 * g);
; #pragma unroll
;         for (int j = 0; j < 4; ++j) { p0[4 * g + j] = b0[j]; p1[4 * g + j] = b1[j]; }
;     }
;     const char* kb[4];
; #pragma unroll
;     for (int dd = 0; dd < 4; ++dd) kb[dd] = K_lds + KB * SHM_K + KSWZ(r32, (dd * 16 + hi * 8) * 2);
; #pragma unroll
;     for (int d0 = 0; d0 < 8; ++d0) { const char* a = kb[d0 & 3] + (d0 >> 2) * 128;
;         bf16x8 b0 = *reinterpret_cast<const bf16x8*>(a);
;         bf16x8 b1 = *reinterpret_cast<const bf16x8*>(a + 32 * 256);
;         p0 = MFMA32(b0, qr[d0], p0);
;         p1 = MFMA32(b1, qr[d0], p1); }
; }
.LBB0_536:
	s_or_b64 exec, exec, s[0:1]
	ds_read_b128 v[86:89], v235 offset:256
	ds_read_b128 v[90:93], v235 offset:288
	ds_read_b128 v[70:73], v235 offset:384
	ds_read_b128 v[74:77], v235 offset:416
	ds_read_b128 v[94:97], v235 offset:320
	ds_read_b128 v[78:81], v235 offset:448
	s_waitcnt vmcnt(0)
	ds_read_b128 v[98:101], v235 offset:352
	ds_read_b128 v[82:85], v235 offset:480
	ds_read_b128 v[66:69], v233 offset:49152
	ds_read_b128 v[102:105], v233 offset:57344
	v_exp_f32_e32 v106, v128
	v_exp_f32_e32 v107, v129
	v_exp_f32_e32 v108, v126
	s_waitcnt lgkmcnt(0)
	v_mfma_f32_32x32x16_bf16 v[86:101], v[66:69], v[158:161], v[86:101]
	v_exp_f32_e32 v109, v127
	v_exp_f32_e32 v110, v124
	v_exp_f32_e32 v111, v125
	v_exp_f32_e32 v112, v122
	v_exp_f32_e32 v113, v123
	v_exp_f32_e32 v120, v120
	v_exp_f32_e32 v121, v121
	v_mfma_f32_32x32x16_bf16 v[70:85], v[102:105], v[158:161], v[70:85]
	ds_read_b128 v[66:69], v234 offset:49152
	ds_read_b128 v[102:105], v234 offset:57344
	v_exp_f32_e32 v118, v118
	v_exp_f32_e32 v119, v119
	v_exp_f32_e32 v116, v116
	v_exp_f32_e32 v117, v117
	v_exp_f32_e32 v114, v114
	v_exp_f32_e32 v115, v115
	s_waitcnt lgkmcnt(1)
	v_mfma_f32_32x32x16_bf16 v[86:101], v[66:69], v[154:157], v[86:101]
	v_add_f32_e32 v200, 0, v176
	v_add_f32_e32 v200, v179, v200
	s_waitcnt lgkmcnt(0)
	v_mfma_f32_32x32x16_bf16 v[70:85], v[102:105], v[154:157], v[70:85]
	v_add_f32_e32 v200, v174, v200
	v_add_f32_e32 v200, v177, v200
	ds_read_b128 v[66:69], v232 offset:49152
	ds_read_b128 v[102:105], v232 offset:57344
	s_waitcnt lgkmcnt(1)
	v_mfma_f32_32x32x16_bf16 v[86:101], v[66:69], v[150:153], v[86:101]
	v_add_f32_e32 v200, v173, v200
	v_add_f32_e32 v200, v175, v200
	s_waitcnt lgkmcnt(0)
	v_mfma_f32_32x32x16_bf16 v[70:85], v[102:105], v[150:153], v[70:85]
	v_add_f32_e32 v200, v171, v200
	v_add_f32_e32 v200, v172, v200
	ds_read_b128 v[66:69], v231 offset:49152
	ds_read_b128 v[102:105], v231 offset:57344
	s_waitcnt lgkmcnt(1)
	v_mfma_f32_32x32x16_bf16 v[86:101], v[66:69], v[146:149], v[86:101]
	v_add_f32_e32 v200, v167, v200
	v_add_f32_e32 v200, v170, v200
	s_waitcnt lgkmcnt(0)
	v_mfma_f32_32x32x16_bf16 v[70:85], v[102:105], v[146:149], v[70:85]
	v_add_f32_e32 v200, v165, v200
	v_add_f32_e32 v200, v168, v200
	ds_read_b128 v[66:69], v233 offset:49280
	ds_read_b128 v[102:105], v233 offset:57472
	s_waitcnt lgkmcnt(1)
	v_mfma_f32_32x32x16_bf16 v[86:101], v[66:69], v[142:145], v[86:101]
	v_add_f32_e32 v200, v163, v200
	v_add_f32_e32 v200, v169, v200
	s_waitcnt lgkmcnt(0)
	v_mfma_f32_32x32x16_bf16 v[70:85], v[102:105], v[142:145], v[70:85]
	v_add_f32_e32 v200, v164, v200
	v_add_f32_e32 v200, v166, v200
	ds_read_b128 v[66:69], v234 offset:49280
	ds_read_b128 v[102:105], v234 offset:57472
	s_waitcnt lgkmcnt(1)
	v_mfma_f32_32x32x16_bf16 v[86:101], v[66:69], v[138:141], v[86:101]
	v_add_f32_e32 v200, v106, v200
	v_add_f32_e32 v200, v107, v200
	s_waitcnt lgkmcnt(0)
	v_mfma_f32_32x32x16_bf16 v[70:85], v[102:105], v[138:141], v[70:85]
	v_add_f32_e32 v200, v108, v200
	v_add_f32_e32 v200, v109, v200
	ds_read_b128 v[66:69], v232 offset:49280
	ds_read_b128 v[102:105], v232 offset:57472
	s_waitcnt lgkmcnt(1)
	v_mfma_f32_32x32x16_bf16 v[86:101], v[66:69], v[134:137], v[86:101]
	v_add_f32_e32 v200, v110, v200
	v_add_f32_e32 v200, v111, v200
	s_waitcnt lgkmcnt(0)
	v_mfma_f32_32x32x16_bf16 v[70:85], v[102:105], v[134:137], v[70:85]
	v_add_f32_e32 v200, v112, v200
	v_add_f32_e32 v200, v113, v200
	ds_read_b128 v[66:69], v231 offset:49280
	ds_read_b128 v[102:105], v231 offset:57472
	s_waitcnt lgkmcnt(1)
	v_mfma_f32_32x32x16_bf16 v[86:101], v[66:69], v[130:133], v[86:101]
	v_add_f32_e32 v200, v120, v200
	v_add_f32_e32 v200, v121, v200
	v_add_f32_e32 v200, v118, v200
	v_add_f32_e32 v200, v119, v200
	s_waitcnt lgkmcnt(0)
	v_mfma_f32_32x32x16_bf16 v[70:85], v[102:105], v[130:133], v[70:85]
	v_add_f32_e32 v200, v116, v200
	v_add_f32_e32 v200, v117, v200
	v_add_f32_e32 v200, v114, v200
	v_add_f32_e32 v239, v115, v200
	v_mov_b32_e32 v240, v239
	s_nop 1
	v_permlane32_swap_b32_e32 v239, v240
	v_cvt_pk_bf16_f32 v66, v176, v179
	v_cvt_pk_bf16_f32 v67, v174, v177
	v_cvt_pk_bf16_f32 v68, v173, v175
	v_cvt_pk_bf16_f32 v69, v171, v172
	v_cvt_pk_bf16_f32 v102, v167, v170
	v_cvt_pk_bf16_f32 v103, v165, v168
	v_cvt_pk_bf16_f32 v104, v163, v169
	v_cvt_pk_bf16_f32 v105, v164, v166
	v_cvt_pk_bf16_f32 v106, v106, v107
	v_cvt_pk_bf16_f32 v107, v108, v109
	v_cvt_pk_bf16_f32 v108, v110, v111
	v_cvt_pk_bf16_f32 v109, v112, v113
	v_cvt_pk_bf16_f32 v110, v120, v121
	v_cvt_pk_bf16_f32 v111, v118, v119
	v_cvt_pk_bf16_f32 v112, v116, v117
	v_cvt_pk_bf16_f32 v113, v114, v115
	s_nop 0
	v_permlane32_swap_b32_e32 v66, v68
	v_permlane32_swap_b32_e32 v67, v69
	v_permlane32_swap_b32_e32 v102, v104
	v_permlane32_swap_b32_e32 v103, v105
	v_permlane32_swap_b32_e32 v106, v108
	v_permlane32_swap_b32_e32 v107, v109
	v_permlane32_swap_b32_e32 v110, v112
	v_permlane32_swap_b32_e32 v111, v113
	v_add_u32_e32 v244, s18, v199
	v_add_u32_e32 v245, s18, v221
	v_add_u32_e32 v114, 1, v244
	v_add_u32_e32 v116, 33, v244
	v_mad_u32_u24 v114, v114, s35, v0
	v_mad_u32_u24 v116, v116, s35, v0
	v_add_u32_e32 v242, 1, v245
	v_lshlrev_b32_e32 v242, 2, v242
	global_load_dwordx4 v[162:165], v114, s[8:9]
	global_load_dwordx4 v[166:169], v116, s[8:9]
	global_load_dwordx4 v[170:173], v114, s[10:11]
	global_load_dwordx4 v[174:177], v116, s[10:11]
	global_load_dword v242, v242, s[4:5]
	ds_read_b64_tr_b16 v[114:115], v227 offset:0
	ds_read_b64_tr_b16 v[116:117], v227 offset:0x800
	ds_read_b64_tr_b16 v[118:119], v227 offset:0x1000
	ds_read_b64_tr_b16 v[120:121], v227 offset:0x1800
	ds_read_b64_tr_b16 v[122:123], v227 offset:0x2000
	ds_read_b64_tr_b16 v[124:125], v227 offset:0x2800
	ds_read_b64_tr_b16 v[126:127], v227 offset:0x3000
	ds_read_b64_tr_b16 v[128:129], v227 offset:0x3800
	s_waitcnt lgkmcnt(0)
; DI void mask_tile(f32x16& p0, f32x16& p1, int dq) {
;     const float NEG = -__builtin_inff();
; #pragma unroll
;     for (int r = 0; r < 16; ++r) {
;         const int c = (r & 3) + 8 * (r >> 2);
;         if ((unsigned)(dq - c) >= WBIG) p0[r] = NEG;
;         if ((unsigned)(dq - c - 32) >= WBIG) p1[r] = NEG;
;     }
; }
; template <int VB>
; DI void pv_tile(f32x16* o, int vb0, bf16x8 pa0, bf16x8 pa1, bf16x8 pa2, bf16x8 pa3) {
;     ...
;     PV_D0(0); PV_D0(1); PV_D0(2); PV_D0(3);
	s_nop 0
	v_mfma_f32_32x32x16_bf16 v[50:65], v[66:69], v[114:117], v[50:65]
	ds_read_b64_tr_b16 v[114:115], v227 offset:0x200
	ds_read_b64_tr_b16 v[116:117], v227 offset:0xa00
	v_mfma_f32_32x32x16_bf16 v[50:65], v[102:105], v[118:121], v[50:65]
	ds_read_b64_tr_b16 v[118:119], v227 offset:0x1200
	ds_read_b64_tr_b16 v[120:121], v227 offset:0x1a00
	v_mfma_f32_32x32x16_bf16 v[50:65], v[106:109], v[122:125], v[50:65]
	ds_read_b64_tr_b16 v[122:123], v227 offset:0x2200
	ds_read_b64_tr_b16 v[124:125], v227 offset:0x2a00
	v_mfma_f32_32x32x16_bf16 v[50:65], v[110:113], v[126:129], v[50:65]
	ds_read_b64_tr_b16 v[126:127], v227 offset:0x3200
	ds_read_b64_tr_b16 v[128:129], v227 offset:0x3a00
	s_waitcnt lgkmcnt(0)
	v_mfma_f32_32x32x16_bf16 v[34:49], v[66:69], v[114:117], v[34:49]
	ds_read_b64_tr_b16 v[114:115], v227 offset:0x400
	ds_read_b64_tr_b16 v[116:117], v227 offset:0xc00
	v_mfma_f32_32x32x16_bf16 v[34:49], v[102:105], v[118:121], v[34:49]
	ds_read_b64_tr_b16 v[118:119], v227 offset:0x1400
	ds_read_b64_tr_b16 v[120:121], v227 offset:0x1c00
	v_mfma_f32_32x32x16_bf16 v[34:49], v[106:109], v[122:125], v[34:49]
	ds_read_b64_tr_b16 v[122:123], v227 offset:0x2400
	ds_read_b64_tr_b16 v[124:125], v227 offset:0x2c00
	v_mfma_f32_32x32x16_bf16 v[34:49], v[110:113], v[126:129], v[34:49]
	ds_read_b64_tr_b16 v[126:127], v227 offset:0x3400
	ds_read_b64_tr_b16 v[128:129], v227 offset:0x3c00
	s_waitcnt lgkmcnt(0)
	v_mfma_f32_32x32x16_bf16 v[18:33], v[66:69], v[114:117], v[18:33]
	ds_read_b64_tr_b16 v[114:115], v227 offset:0x600
	ds_read_b64_tr_b16 v[116:117], v227 offset:0xe00
	v_mfma_f32_32x32x16_bf16 v[18:33], v[102:105], v[118:121], v[18:33]
	ds_read_b64_tr_b16 v[118:119], v227 offset:0x1600
	ds_read_b64_tr_b16 v[120:121], v227 offset:0x1e00
	v_mfma_f32_32x32x16_bf16 v[18:33], v[106:109], v[122:125], v[18:33]
	ds_read_b64_tr_b16 v[122:123], v227 offset:0x2600
	ds_read_b64_tr_b16 v[124:125], v227 offset:0x2e00
	v_mfma_f32_32x32x16_bf16 v[18:33], v[110:113], v[126:129], v[18:33]
	ds_read_b64_tr_b16 v[126:127], v227 offset:0x3600
	ds_read_b64_tr_b16 v[128:129], v227 offset:0x3e00
	s_waitcnt lgkmcnt(0)
	v_mfma_f32_32x32x16_bf16 v[2:17], v[66:69], v[114:117], v[2:17]
	s_cmp_le_i32 s18, s31
	v_mfma_f32_32x32x16_bf16 v[2:17], v[102:105], v[118:121], v[2:17]
	v_mfma_f32_32x32x16_bf16 v[2:17], v[106:109], v[122:125], v[2:17]
	v_mfma_f32_32x32x16_bf16 v[2:17], v[110:113], v[126:129], v[2:17]
	s_cbranch_scc1 .LBB0_538
	v_add_u32_e32 v66, 0x4000007b, v238
	v_cmp_gt_u32_e32 vcc, 2.0, v66
	v_add_u32_e32 v66, 0x5b, v238
	s_nop 0
	v_cndmask_b32_e32 v86, v214, v86, vcc
	v_cmp_lt_u32_e32 vcc, s68, v66
	v_add_u32_e32 v66, 0x7a, v238
	s_nop 0
	v_cndmask_b32_e32 v70, v214, v70, vcc
	v_cmp_lt_u32_e32 vcc, s68, v66
	v_add_u32_e32 v66, 0x5a, v238
	s_nop 0
	v_cndmask_b32_e32 v87, v214, v87, vcc
	v_cmp_lt_u32_e32 vcc, s68, v66
	v_add_u32_e32 v66, 0x79, v238
	s_nop 0
	v_cndmask_b32_e32 v71, v214, v71, vcc
	v_cmp_lt_u32_e32 vcc, s68, v66
	v_add_u32_e32 v66, 0x59, v238
	s_nop 0
	v_cndmask_b32_e32 v88, v214, v88, vcc
	v_cmp_lt_u32_e32 vcc, s68, v66
	v_add_u32_e32 v66, 0x78, v238
	s_nop 0
	v_cndmask_b32_e32 v72, v214, v72, vcc
	v_cmp_lt_u32_e32 vcc, s68, v66
	v_add_u32_e32 v66, 0x58, v238
	s_nop 0
	v_cndmask_b32_e32 v89, v214, v89, vcc
	v_cmp_lt_u32_e32 vcc, s68, v66
	v_add_u32_e32 v66, 0x73, v238
	s_nop 0
	v_cndmask_b32_e32 v73, v214, v73, vcc
	v_cmp_lt_u32_e32 vcc, s68, v66
	v_add_u32_e32 v66, 0x53, v238
	s_nop 0
	v_cndmask_b32_e32 v90, v214, v90, vcc
	v_cmp_lt_u32_e32 vcc, s68, v66
	v_add_u32_e32 v66, 0x72, v238
	s_nop 0
	v_cndmask_b32_e32 v74, v214, v74, vcc
	v_cmp_lt_u32_e32 vcc, s68, v66
	v_add_u32_e32 v66, 0x52, v238
	s_nop 0
	v_cndmask_b32_e32 v91, v214, v91, vcc
	v_cmp_lt_u32_e32 vcc, s68, v66
	v_add_u32_e32 v66, 0x71, v238
	s_nop 0
	v_cndmask_b32_e32 v75, v214, v75, vcc
	v_cmp_lt_u32_e32 vcc, s68, v66
	v_add_u32_e32 v66, 0x51, v238
	s_nop 0
	v_cndmask_b32_e32 v92, v214, v92, vcc
	v_cmp_lt_u32_e32 vcc, s68, v66
	v_add_u32_e32 v66, 0x70, v238
	s_nop 0
	v_cndmask_b32_e32 v76, v214, v76, vcc
	v_cmp_lt_u32_e32 vcc, s68, v66
	v_add_u32_e32 v66, 0x50, v238
	s_nop 0
	v_cndmask_b32_e32 v93, v214, v93, vcc
	v_cmp_lt_u32_e32 vcc, s68, v66
	v_add_u32_e32 v66, 0x6b, v238
	s_nop 0
	v_cndmask_b32_e32 v77, v214, v77, vcc
	v_cmp_lt_u32_e32 vcc, s68, v66
	v_add_u32_e32 v66, 0x4b, v238
	s_nop 0
	v_cndmask_b32_e32 v94, v214, v94, vcc
	v_cmp_lt_u32_e32 vcc, s68, v66
	v_add_u32_e32 v66, 0x6a, v238
	s_nop 0
	v_cndmask_b32_e32 v78, v214, v78, vcc
	v_cmp_lt_u32_e32 vcc, s68, v66
	v_add_u32_e32 v66, 0x4a, v238
	s_nop 0
	v_cndmask_b32_e32 v95, v214, v95, vcc
	v_cmp_lt_u32_e32 vcc, s68, v66
	v_add_u32_e32 v66, 0x69, v238
	s_nop 0
	v_cndmask_b32_e32 v79, v214, v79, vcc
	v_cmp_lt_u32_e32 vcc, s68, v66
	v_add_u32_e32 v66, 0x49, v238
	s_nop 0
	v_cndmask_b32_e32 v96, v214, v96, vcc
	v_cmp_lt_u32_e32 vcc, s68, v66
	v_add_u32_e32 v66, 0x68, v238
	s_nop 0
	v_cndmask_b32_e32 v80, v214, v80, vcc
	v_cmp_lt_u32_e32 vcc, s68, v66
	v_add_u32_e32 v66, 0x48, v238
	s_nop 0
	v_cndmask_b32_e32 v97, v214, v97, vcc
	v_cmp_lt_u32_e32 vcc, s68, v66
	v_add_u32_e32 v66, 0x63, v238
	s_nop 0
	v_cndmask_b32_e32 v81, v214, v81, vcc
	v_cmp_lt_u32_e32 vcc, s68, v66
	v_add_u32_e32 v66, 0x43, v238
	s_nop 0
	v_cndmask_b32_e32 v98, v214, v98, vcc
	v_cmp_lt_u32_e32 vcc, s68, v66
	v_add_u32_e32 v66, 0x62, v238
	s_nop 0
	v_cndmask_b32_e32 v82, v214, v82, vcc
	v_cmp_lt_u32_e32 vcc, s68, v66
	v_add_u32_e32 v66, 0x42, v238
	s_nop 0
	v_cndmask_b32_e32 v99, v214, v99, vcc
	v_cmp_lt_u32_e32 vcc, s68, v66
	v_add_u32_e32 v66, 0x61, v238
	s_nop 0
	v_cndmask_b32_e32 v83, v214, v83, vcc
	v_cmp_lt_u32_e32 vcc, s68, v66
	v_add_u32_e32 v66, 0x41, v238
	s_nop 0
	v_cndmask_b32_e32 v100, v214, v100, vcc
	v_cmp_lt_u32_e32 vcc, s68, v66
	v_add_u32_e32 v66, 0x60, v238
	s_nop 0
	v_cndmask_b32_e32 v84, v214, v84, vcc
	v_cmp_lt_u32_e32 vcc, s68, v66
	v_add_u32_e32 v66, 64, v238
	s_nop 0
	v_cndmask_b32_e32 v101, v214, v101, vcc
	v_cmp_lt_u32_e32 vcc, s68, v66
	s_nop 1
	v_cndmask_b32_e32 v85, v214, v85, vcc

; #define MFMA32(a, b, c) __builtin_amdgcn_mfma_f32_32x32x16_bf16((a), (b), (c), 0, 0, 0)
; DI void finishSM(f32x16& p0, f32x16& p1, float alpha, float& l_reg, bf16x8& pa0, bf16x8& pa1, bf16x8& pa2, bf16x8& pa3) {
; #pragma unroll
;     for (int r = 0; r < 16; ++r) p1[r] = __builtin_amdgcn_exp2f(p1[r]);
;     float ps = 0;
; #pragma unroll
;     for (int r = 0; r < 16; ++r) ps += p0[r];
; #pragma unroll
;     for (int r = 0; r < 16; ++r) ps += p1[r];
;     { auto rr = __builtin_amdgcn_permlane32_swap(__float_as_uint(ps), __float_as_uint(ps), false, false);
;       ps = __uint_as_float(rr[0]) + __uint_as_float(rr[1]); }
;     l_reg = l_reg * alpha + ps;
;     ...
;     PK4(p0, 0, pa0); PK4(p0, 8, pa1); PK4(p1, 0, pa2); PK4(p1, 8, pa3);
;     ...
; }
; template <int KB>
; DI void qkt(f32x16& p0, f32x16& p1, const char* K_lds, int r32, int hi, const bf16x8* qr, const float* bb) {
; #pragma unroll
;     for (int g = 0; g < 4; ++g) {
;         const f32x4 b0 = *(const f32x4*)(bb + KB * 64 + 8 * g), b1 = *(const f32x4*)(bb + KB * 64 + 32 + 8 * g);
; #pragma unroll
;         for (int j = 0; j < 4; ++j) { p0[4 * g + j] = b0[j]; p1[4 * g + j] = b1[j]; }
;     }
;     const char* kb[4];
; #pragma unroll
;     for (int dd = 0; dd < 4; ++dd) kb[dd] = K_lds + KB * SHM_K + KSWZ(r32, (dd * 16 + hi * 8) * 2);
; #pragma unroll
;     for (int d0 = 0; d0 < 8; ++d0) { const char* a = kb[d0 & 3] + (d0 >> 2) * 128;
;         bf16x8 b0 = *reinterpret_cast<const bf16x8*>(a);
;         bf16x8 b1 = *reinterpret_cast<const bf16x8*>(a + 32 * 256);
;         p0 = MFMA32(b0, qr[d0], p0);
;         p1 = MFMA32(b1, qr[d0], p1); }
; }
.Lfa_c2_skip:
	ds_read_b128 v[114:117], v235
	ds_read_b128 v[118:121], v235 offset:32
	ds_read_b128 v[98:101], v235 offset:128
	ds_read_b128 v[102:105], v235 offset:160
	ds_read_b128 v[122:125], v235 offset:64
	ds_read_b128 v[106:109], v235 offset:192
	ds_read_b128 v[126:129], v235 offset:96
	ds_read_b128 v[110:113], v235 offset:224
	ds_read_b128 v[82:85], v233 offset:32768
	ds_read_b128 v[182:185], v233 offset:40960
	v_exp_f32_e32 v87, v87
	v_exp_f32_e32 v88, v88
	v_exp_f32_e32 v89, v89
	s_waitcnt lgkmcnt(1)
	v_mfma_f32_32x32x16_bf16 v[114:129], v[82:85], v[158:161], v[114:129]
	v_exp_f32_e32 v90, v90
	v_exp_f32_e32 v91, v91
	v_exp_f32_e32 v92, v92
	v_exp_f32_e32 v93, v93
	v_exp_f32_e32 v94, v94
	s_waitcnt lgkmcnt(0)
	v_mfma_f32_32x32x16_bf16 v[98:113], v[182:185], v[158:161], v[98:113]
	ds_read_b128 v[82:85], v234 offset:32768
	ds_read_b128 v[182:185], v234 offset:40960
	s_waitcnt lgkmcnt(1)
	v_mfma_f32_32x32x16_bf16 v[114:129], v[82:85], v[154:157], v[114:129]
	v_add_f32_e32 v200, 0, v66
	v_add_f32_e32 v200, v67, v200
	s_waitcnt lgkmcnt(0)
	v_mfma_f32_32x32x16_bf16 v[98:113], v[182:185], v[154:157], v[98:113]
	v_add_f32_e32 v200, v68, v200
	v_add_f32_e32 v200, v69, v200
	ds_read_b128 v[82:85], v232 offset:32768
	ds_read_b128 v[182:185], v232 offset:40960
	s_waitcnt lgkmcnt(1)
	v_mfma_f32_32x32x16_bf16 v[114:129], v[82:85], v[150:153], v[114:129]
	v_add_f32_e32 v200, v70, v200
	v_add_f32_e32 v200, v71, v200
	s_waitcnt lgkmcnt(0)
	v_mfma_f32_32x32x16_bf16 v[98:113], v[182:185], v[150:153], v[98:113]
	v_add_f32_e32 v200, v72, v200
	v_add_f32_e32 v200, v73, v200
	ds_read_b128 v[82:85], v231 offset:32768
	ds_read_b128 v[182:185], v231 offset:40960
	s_waitcnt lgkmcnt(1)
	v_mfma_f32_32x32x16_bf16 v[114:129], v[82:85], v[146:149], v[114:129]
	v_add_f32_e32 v200, v74, v200
	v_add_f32_e32 v200, v75, v200
	s_waitcnt lgkmcnt(0)
	v_mfma_f32_32x32x16_bf16 v[98:113], v[182:185], v[146:149], v[98:113]
	v_add_f32_e32 v200, v76, v200
	v_add_f32_e32 v200, v77, v200
	ds_read_b128 v[82:85], v233 offset:32896
	ds_read_b128 v[182:185], v233 offset:41088
	s_waitcnt lgkmcnt(1)
	v_mfma_f32_32x32x16_bf16 v[114:129], v[82:85], v[142:145], v[114:129]
	v_add_f32_e32 v200, v78, v200
	v_add_f32_e32 v200, v79, v200
	s_waitcnt lgkmcnt(0)
	v_mfma_f32_32x32x16_bf16 v[98:113], v[182:185], v[142:145], v[98:113]
	v_add_f32_e32 v200, v80, v200
	v_add_f32_e32 v200, v81, v200
	ds_read_b128 v[82:85], v234 offset:32896
	ds_read_b128 v[182:185], v234 offset:41088
	s_waitcnt lgkmcnt(1)
	v_mfma_f32_32x32x16_bf16 v[114:129], v[82:85], v[138:141], v[114:129]
	s_waitcnt lgkmcnt(0)
	v_mfma_f32_32x32x16_bf16 v[98:113], v[182:185], v[138:141], v[98:113]
	ds_read_b128 v[82:85], v232 offset:32896
	ds_read_b128 v[182:185], v232 offset:41088
	s_waitcnt lgkmcnt(1)
	v_mfma_f32_32x32x16_bf16 v[114:129], v[82:85], v[134:137], v[114:129]
	s_waitcnt lgkmcnt(0)
	v_mfma_f32_32x32x16_bf16 v[98:113], v[182:185], v[134:137], v[98:113]
	ds_read_b128 v[82:85], v231 offset:32896
	ds_read_b128 v[182:185], v231 offset:41088
	s_waitcnt lgkmcnt(1)
	v_mfma_f32_32x32x16_bf16 v[114:129], v[82:85], v[130:133], v[114:129]
	v_exp_f32_e32 v85, v97
	v_exp_f32_e32 v97, v178
	v_exp_f32_e32 v82, v86
	v_exp_f32_e32 v83, v95
	v_exp_f32_e32 v84, v96
	v_exp_f32_e32 v86, v179
	v_add_f32_e32 v178, v82, v200
	v_add_f32_e32 v178, v83, v178
	v_add_f32_e32 v178, v84, v178
	v_add_f32_e32 v178, v85, v178
	v_add_f32_e32 v178, v86, v178
	v_add_f32_e32 v178, v87, v178
	v_add_f32_e32 v178, v88, v178
	v_add_f32_e32 v178, v89, v178
	v_add_f32_e32 v178, v90, v178
	v_exp_f32_e32 v95, v180
	v_add_f32_e32 v178, v91, v178
	s_waitcnt lgkmcnt(0)
	v_mfma_f32_32x32x16_bf16 v[98:113], v[182:185], v[130:133], v[98:113]
	v_exp_f32_e32 v96, v181
	v_add_f32_e32 v178, v92, v178
	v_add_f32_e32 v178, v93, v178
	v_add_f32_e32 v178, v94, v178
	v_add_f32_e32 v178, v95, v178
	v_add_f32_e32 v178, v96, v178
	v_add_f32_e32 v246, v97, v178
	v_mov_b32_e32 v247, v246
	v_cvt_pk_bf16_f32 v178, v66, v67
	v_cvt_pk_bf16_f32 v179, v68, v69
	v_cvt_pk_bf16_f32 v180, v70, v71
	v_cvt_pk_bf16_f32 v181, v72, v73
	v_cvt_pk_bf16_f32 v182, v74, v75
	v_cvt_pk_bf16_f32 v183, v76, v77
	v_cvt_pk_bf16_f32 v184, v78, v79
	v_cvt_pk_bf16_f32 v185, v80, v81
	v_cvt_pk_bf16_f32 v186, v82, v83
	v_cvt_pk_bf16_f32 v187, v84, v85
	v_cvt_pk_bf16_f32 v188, v86, v87
	v_cvt_pk_bf16_f32 v189, v88, v89
	v_cvt_pk_bf16_f32 v190, v90, v91
	v_cvt_pk_bf16_f32 v191, v92, v93
	v_cvt_pk_bf16_f32 v192, v94, v95
	v_cvt_pk_bf16_f32 v193, v96, v97
	s_nop 1
	v_permlane32_swap_b32_e32 v246, v247
	v_permlane32_swap_b32_e32 v178, v180
	v_permlane32_swap_b32_e32 v179, v181
	v_permlane32_swap_b32_e32 v182, v184
	v_permlane32_swap_b32_e32 v183, v185
	v_permlane32_swap_b32_e32 v186, v188
	v_permlane32_swap_b32_e32 v187, v189
	v_permlane32_swap_b32_e32 v190, v192
	v_permlane32_swap_b32_e32 v191, v193
